# baseline (speedup 1.0000x reference)
; __device__ __forceinline__ void unpack8(u32x4 w, float (&o)[8]) { o[0] = bflo(w.x); o[1] = bfhi(w.x); o[2] = bflo(w.y); o[3] = bfhi(w.y); o[4] = bflo(w.z); o[5] = bfhi(w.z); o[6] = bflo(w.w); o[7] = bfhi(w.w); }
; __device__ __forceinline__ void e1_phase(const bf16* P, const float* conv_w, const float* mu, const float* cache_conv, const float* cache_shift, bf16* MIX, bf16* LIN, float* out, int gw, int NGW, int lane) {
;     ...
; #pragma unroll 2
;             for (int j = 0; j < 8; ++j) {
;                 const size_t m = (size_t)(m0 + j); float gb[8], gc[8], hc[8], u[8], y[8];
;                 unpack8(*(const u32x4*)(P + m * PROJ + c0), gb); unpack8(*(const u32x4*)(P + m * PROJ + CONVC + c0), gc); unpack8(*(const u32x4*)(P + m * PROJ + 2 * CONVC + c0), hc);
.LBB0_511:
	s_lshl_b32 s16, s18, 2
	s_add_u32 s16, s12, s16
	s_addc_u32 s51, s13, 0
	s_lshl_b64 s[18:19], s[54:55], 2
	s_add_u32 s56, s16, s18
	s_addc_u32 s57, s51, s19
	s_and_b32 s54, s37, -8
	s_ashr_i32 s55, s54, 31
	s_lshl_b64 s[18:19], s[54:55], 12
	s_add_u32 s18, s14, s18
	s_addc_u32 s19, s15, s19
	s_mul_i32 s51, s54, 0x3240
	s_mul_hi_i32 s16, s54, 0x3240
	s_add_u32 s54, s14, s51
	s_addc_u32 s55, s15, s16
	v_lshl_add_u64 v[70:71], v[54:55], 2, s[56:57]
	v_lshl_add_u64 v[118:119], s[54:55], 0, v[64:65]
	v_add_co_u32_e32 v118, vcc, 0xa8c0000, v118
	s_nop 1
	v_addc_co_u32_e32 v119, vcc, 0, v119, vcc
	v_add_co_u32_e32 v120, vcc, 0x1000, v118
	s_nop 1
	v_addc_co_u32_e32 v121, vcc, 0, v119, vcc
	global_load_dwordx4 v[122:125], v[118:119], off
	global_load_dwordx4 v[126:129], v[118:119], off offset:2048
	global_load_dwordx4 v[130:133], v[120:121], off
	v_add_co_u32_e32 v118, vcc, 0x3240, v118
	s_nop 1
	v_addc_co_u32_e32 v119, vcc, 0, v119, vcc
	v_add_co_u32_e32 v120, vcc, 0x3240, v120
	s_nop 1
	v_addc_co_u32_e32 v121, vcc, 0, v121, vcc
	global_load_dwordx4 v[134:137], v[118:119], off
	global_load_dwordx4 v[122:125], v[118:119], off offset:2048
	global_load_dwordx4 v[126:129], v[120:121], off
	v_add_co_u32_e32 v118, vcc, 0x3240, v118
	s_nop 1
	v_addc_co_u32_e32 v119, vcc, 0, v119, vcc
	v_add_co_u32_e32 v120, vcc, 0x3240, v120
	s_nop 1
	v_addc_co_u32_e32 v121, vcc, 0, v121, vcc
	global_load_dwordx4 v[130:133], v[118:119], off
	global_load_dwordx4 v[134:137], v[118:119], off offset:2048
	global_load_dwordx4 v[122:125], v[120:121], off
	v_add_co_u32_e32 v118, vcc, 0x3240, v118
	s_nop 1
	v_addc_co_u32_e32 v119, vcc, 0, v119, vcc
	v_add_co_u32_e32 v120, vcc, 0x3240, v120
	s_nop 1
	v_addc_co_u32_e32 v121, vcc, 0, v121, vcc
	global_load_dwordx4 v[126:129], v[118:119], off
	global_load_dwordx4 v[130:133], v[118:119], off offset:2048
	global_load_dwordx4 v[134:137], v[120:121], off
	v_add_co_u32_e32 v118, vcc, 0x3240, v118
	s_nop 1
	v_addc_co_u32_e32 v119, vcc, 0, v119, vcc
	v_add_co_u32_e32 v120, vcc, 0x3240, v120
	s_nop 1
	v_addc_co_u32_e32 v121, vcc, 0, v121, vcc
	global_load_dwordx4 v[122:125], v[118:119], off
	global_load_dwordx4 v[126:129], v[118:119], off offset:2048
	global_load_dwordx4 v[130:133], v[120:121], off
	v_add_co_u32_e32 v118, vcc, 0x3240, v118
	s_nop 1
	v_addc_co_u32_e32 v119, vcc, 0, v119, vcc
	v_add_co_u32_e32 v120, vcc, 0x3240, v120
	s_nop 1
	v_addc_co_u32_e32 v121, vcc, 0, v121, vcc
	global_load_dwordx4 v[134:137], v[118:119], off
	global_load_dwordx4 v[122:125], v[118:119], off offset:2048
	global_load_dwordx4 v[126:129], v[120:121], off
	v_add_co_u32_e32 v118, vcc, 0x3240, v118
	s_nop 1
	v_addc_co_u32_e32 v119, vcc, 0, v119, vcc
	v_add_co_u32_e32 v120, vcc, 0x3240, v120
	s_nop 1
	v_addc_co_u32_e32 v121, vcc, 0, v121, vcc
	global_load_dwordx4 v[130:133], v[118:119], off
	global_load_dwordx4 v[134:137], v[118:119], off offset:2048
	global_load_dwordx4 v[122:125], v[120:121], off
	v_add_co_u32_e32 v118, vcc, 0x3240, v118
	s_nop 1
	v_addc_co_u32_e32 v119, vcc, 0, v119, vcc
	v_add_co_u32_e32 v120, vcc, 0x3240, v120
	s_nop 1
	v_addc_co_u32_e32 v121, vcc, 0, v121, vcc
	global_load_dwordx4 v[126:129], v[118:119], off
	global_load_dwordx4 v[130:133], v[118:119], off offset:2048
	global_load_dwordx4 v[134:137], v[120:121], off
	s_add_i32 s51, s65, -2
	s_waitcnt vmcnt(0)
	v_mov_b32_e32 v72, v42
	v_mov_b32_e32 v73, v12
	v_mov_b32_e32 v12, v43
	v_mov_b32_e32 v42, v40
	v_mov_b32_e32 v43, v10
	v_mov_b32_e32 v10, v41
	v_mov_b32_e32 v74, v38
	v_mov_b32_e32 v75, v16
	v_mov_b32_e32 v16, v39
	v_mov_b32_e32 v76, v36
	v_mov_b32_e32 v77, v14
	v_mov_b32_e32 v14, v37
	s_sub_i32 s56, s64, s65
	s_mov_b32 s57, 0
	s_branch .LBB0_513

; __device__ __forceinline__ void unpack8(u32x4 w, float (&o)[8]) { o[0] = bflo(w.x); o[1] = bfhi(w.x); o[2] = bflo(w.y); o[3] = bfhi(w.y); o[4] = bflo(w.z); o[5] = bfhi(w.z); o[6] = bflo(w.w); o[7] = bfhi(w.w); }
; __device__ __forceinline__ void e1_phase(const bf16* P, const float* conv_w, const float* mu, const float* cache_conv, const float* cache_shift, bf16* MIX, bf16* LIN, float* out, int gw, int NGW, int lane) {
;     ...
; #pragma unroll 2
;             for (int j = 0; j < 8; ++j) {
;                 const size_t m = (size_t)(m0 + j); float cur[8], o[8];
;                 unpack8(*(const u32x4*)(P + m * PROJ + 3 * CONVC + j0), cur);
.LBB0_528:
	s_mul_i32 s52, s37, 0x3240
	s_mul_hi_i32 s53, s37, 0x3240
	s_add_u32 s52, s33, s52
	s_addc_u32 s53, s35, s53
	v_lshl_add_u64 v[118:119], v[44:45], 1, s[52:53]
	v_add_co_u32_e32 v118, vcc, 0x1800, v118
	s_nop 1
	v_addc_co_u32_e32 v119, vcc, 0, v119, vcc
	global_load_dwordx4 v[122:125], v[118:119], off
	v_add_co_u32_e32 v118, vcc, 0x3240, v118
	s_nop 1
	v_addc_co_u32_e32 v119, vcc, 0, v119, vcc
	global_load_dwordx4 v[126:129], v[118:119], off
	v_add_co_u32_e32 v118, vcc, 0x3240, v118
	s_nop 1
	v_addc_co_u32_e32 v119, vcc, 0, v119, vcc
	global_load_dwordx4 v[130:133], v[118:119], off
	v_add_co_u32_e32 v118, vcc, 0x3240, v118
	s_nop 1
	v_addc_co_u32_e32 v119, vcc, 0, v119, vcc
	global_load_dwordx4 v[134:137], v[118:119], off
	v_add_co_u32_e32 v118, vcc, 0x3240, v118
	s_nop 1
	v_addc_co_u32_e32 v119, vcc, 0, v119, vcc
	global_load_dwordx4 v[122:125], v[118:119], off
	v_add_co_u32_e32 v118, vcc, 0x3240, v118
	s_nop 1
	v_addc_co_u32_e32 v119, vcc, 0, v119, vcc
	global_load_dwordx4 v[126:129], v[118:119], off
	v_add_co_u32_e32 v118, vcc, 0x3240, v118
	s_nop 1
	v_addc_co_u32_e32 v119, vcc, 0, v119, vcc
	global_load_dwordx4 v[130:133], v[118:119], off
	v_add_co_u32_e32 v118, vcc, 0x3240, v118
	s_nop 1
	v_addc_co_u32_e32 v119, vcc, 0, v119, vcc
	global_load_dwordx4 v[134:137], v[118:119], off
	s_mov_b32 s16, 0
	s_branch .LBB0_530
